# prologue: serial per-lane max-abs(rpb) loop (1395 dependent loads) replaced by full-wave coalesced sweep + butterfly max
# speedup vs baseline: 1.1564x; 1.1424x over previous
; DI void prologue_phase(const Params& p, char* smem) {
;     ...
;         for (int i = 0; i < 64; ++i) { c = fmaxf(c, fabsf(p.gqn[l * 64 + i])); d2 = fmaxf(d2, fabsf(p.gkn[l * 64 + i])); e2 = fmaxf(e2, fabsf(p.nqn[l * 64 + i])); f2 = fmaxf(f2, fabsf(p.nkn[l * 64 + i])); }
;         for (int i = 0; i < 6 * 465; ++i) g = fmaxf(g, fabsf(p.rpb[(size_t)l * 6 * 465 + i]));
.LBB0_343:
	v_lshl_add_u64 v[80:81], v[70:71], 0, s[8:9]
	v_lshl_add_u64 v[84:85], v[74:75], 0, s[8:9]
	v_lshl_add_u64 v[88:89], v[76:77], 0, s[8:9]
	v_lshl_add_u64 v[92:93], v[72:73], 0, s[8:9]
	global_load_dwordx4 v[80:83], v[80:81], off
	s_nop 0
	global_load_dwordx4 v[84:87], v[84:85], off
	s_nop 0
	global_load_dwordx4 v[88:91], v[88:89], off
	s_nop 0
	global_load_dwordx4 v[92:95], v[92:93], off
	s_add_u32 s8, s8, 16
	s_addc_u32 s9, s9, 0
	s_cmpk_eq_i32 s8, 0x100
	s_waitcnt vmcnt(3)
	v_max3_f32 v66, v69, |v80|, |v81|
	s_waitcnt vmcnt(2)
	v_max3_f32 v67, v67, |v84|, |v85|
	s_waitcnt vmcnt(1)
	v_max3_f32 v65, v65, |v88|, |v89|
	s_waitcnt vmcnt(0)
	v_max3_f32 v68, v78, |v92|, |v93|
	v_max3_f32 v69, v66, |v82|, |v83|
	v_max3_f32 v67, v67, |v86|, |v87|
	v_max3_f32 v65, v65, |v90|, |v91|
	v_max3_f32 v78, v68, |v94|, |v95|
	s_cbranch_scc0 .LBB0_343
	s_load_dwordx2 s[34:35], s[0:1], 0xa0
	s_mov_b64 s[8:9], exec
	s_mov_b64 exec, -1
	v_lshlrev_b32_e32 v96, 2, v205
	v_add_u32_e32 v98, 0x1000, v96
	v_add_u32_e32 v99, 0x2000, v96
	v_add_u32_e32 v97, 0x2b00, v96
	v_min_u32_e32 v97, 0x2b94, v97
	s_waitcnt lgkmcnt(0)
	global_load_dword v100, v96, s[34:35]
	global_load_dword v101, v96, s[34:35] offset:256
	global_load_dword v102, v96, s[34:35] offset:512
	global_load_dword v103, v96, s[34:35] offset:768
	global_load_dword v104, v96, s[34:35] offset:1024
	global_load_dword v105, v96, s[34:35] offset:1280
	global_load_dword v106, v96, s[34:35] offset:1536
	global_load_dword v107, v96, s[34:35] offset:1792
	global_load_dword v108, v96, s[34:35] offset:2048
	global_load_dword v109, v96, s[34:35] offset:2304
	global_load_dword v110, v96, s[34:35] offset:2560
	global_load_dword v111, v96, s[34:35] offset:2816
	global_load_dword v112, v96, s[34:35] offset:3072
	global_load_dword v113, v96, s[34:35] offset:3328
	global_load_dword v114, v96, s[34:35] offset:3584
	global_load_dword v115, v96, s[34:35] offset:3840
	global_load_dword v116, v98, s[34:35]
	global_load_dword v117, v98, s[34:35] offset:256
	global_load_dword v118, v98, s[34:35] offset:512
	global_load_dword v119, v98, s[34:35] offset:768
	global_load_dword v120, v98, s[34:35] offset:1024
	global_load_dword v121, v98, s[34:35] offset:1280
	global_load_dword v122, v98, s[34:35] offset:1536
	global_load_dword v123, v98, s[34:35] offset:1792
	global_load_dword v124, v98, s[34:35] offset:2048
	global_load_dword v125, v98, s[34:35] offset:2304
	global_load_dword v126, v98, s[34:35] offset:2560
	global_load_dword v127, v98, s[34:35] offset:2816
	global_load_dword v128, v98, s[34:35] offset:3072
	global_load_dword v129, v98, s[34:35] offset:3328
	global_load_dword v130, v98, s[34:35] offset:3584
	global_load_dword v131, v98, s[34:35] offset:3840
	global_load_dword v132, v99, s[34:35]
	global_load_dword v133, v99, s[34:35] offset:256
	global_load_dword v134, v99, s[34:35] offset:512
	global_load_dword v135, v99, s[34:35] offset:768
	global_load_dword v136, v99, s[34:35] offset:1024
	global_load_dword v137, v99, s[34:35] offset:1280
	global_load_dword v138, v99, s[34:35] offset:1536
	global_load_dword v139, v99, s[34:35] offset:1792
	global_load_dword v140, v99, s[34:35] offset:2048
	global_load_dword v141, v99, s[34:35] offset:2304
	global_load_dword v142, v99, s[34:35] offset:2560
	global_load_dword v143, v97, s[34:35]
	s_add_u32 s34, s34, 0x2b98
	s_addc_u32 s35, s35, 0
	s_waitcnt vmcnt(0)
	v_max3_f32 v144, |v100|, |v101|, |v102|
	v_max3_f32 v144, v144, |v103|, |v104|
	v_max3_f32 v144, v144, |v105|, |v106|
	v_max3_f32 v144, v144, |v107|, |v108|
	v_max3_f32 v144, v144, |v109|, |v110|
	v_max3_f32 v144, v144, |v111|, |v112|
	v_max3_f32 v144, v144, |v113|, |v114|
	v_max3_f32 v144, v144, |v115|, |v116|
	v_max3_f32 v144, v144, |v117|, |v118|
	v_max3_f32 v144, v144, |v119|, |v120|
	v_max3_f32 v144, v144, |v121|, |v122|
	v_max3_f32 v144, v144, |v123|, |v124|
	v_max3_f32 v144, v144, |v125|, |v126|
	v_max3_f32 v144, v144, |v127|, |v128|
	v_max3_f32 v144, v144, |v129|, |v130|
	v_max3_f32 v144, v144, |v131|, |v132|
	v_max3_f32 v144, v144, |v133|, |v134|
	v_max3_f32 v144, v144, |v135|, |v136|
	v_max3_f32 v144, v144, |v137|, |v138|
	v_max3_f32 v144, v144, |v139|, |v140|
	v_max3_f32 v144, v144, |v141|, |v142|
	v_max_f32_e64 v144, v144, |v143|
	global_load_dword v100, v96, s[34:35]
	global_load_dword v101, v96, s[34:35] offset:256
	global_load_dword v102, v96, s[34:35] offset:512
	global_load_dword v103, v96, s[34:35] offset:768
	global_load_dword v104, v96, s[34:35] offset:1024
	global_load_dword v105, v96, s[34:35] offset:1280
	global_load_dword v106, v96, s[34:35] offset:1536
	global_load_dword v107, v96, s[34:35] offset:1792
	global_load_dword v108, v96, s[34:35] offset:2048
	global_load_dword v109, v96, s[34:35] offset:2304
	global_load_dword v110, v96, s[34:35] offset:2560
	global_load_dword v111, v96, s[34:35] offset:2816
	global_load_dword v112, v96, s[34:35] offset:3072
	global_load_dword v113, v96, s[34:35] offset:3328
	global_load_dword v114, v96, s[34:35] offset:3584
	global_load_dword v115, v96, s[34:35] offset:3840
	global_load_dword v116, v98, s[34:35]
	global_load_dword v117, v98, s[34:35] offset:256
	global_load_dword v118, v98, s[34:35] offset:512
	global_load_dword v119, v98, s[34:35] offset:768
	global_load_dword v120, v98, s[34:35] offset:1024
	global_load_dword v121, v98, s[34:35] offset:1280
	global_load_dword v122, v98, s[34:35] offset:1536
	global_load_dword v123, v98, s[34:35] offset:1792
	global_load_dword v124, v98, s[34:35] offset:2048
	global_load_dword v125, v98, s[34:35] offset:2304
	global_load_dword v126, v98, s[34:35] offset:2560
	global_load_dword v127, v98, s[34:35] offset:2816
	global_load_dword v128, v98, s[34:35] offset:3072
	global_load_dword v129, v98, s[34:35] offset:3328
	global_load_dword v130, v98, s[34:35] offset:3584
	global_load_dword v131, v98, s[34:35] offset:3840
	global_load_dword v132, v99, s[34:35]
	global_load_dword v133, v99, s[34:35] offset:256
	global_load_dword v134, v99, s[34:35] offset:512
	global_load_dword v135, v99, s[34:35] offset:768
	global_load_dword v136, v99, s[34:35] offset:1024
	global_load_dword v137, v99, s[34:35] offset:1280
	global_load_dword v138, v99, s[34:35] offset:1536
	global_load_dword v139, v99, s[34:35] offset:1792
	global_load_dword v140, v99, s[34:35] offset:2048
	global_load_dword v141, v99, s[34:35] offset:2304
	global_load_dword v142, v99, s[34:35] offset:2560
	global_load_dword v143, v97, s[34:35]
	s_add_u32 s34, s34, 0x2b98
	s_addc_u32 s35, s35, 0
	s_waitcnt vmcnt(0)
; DI void prologue_phase(const Params& p, char* smem) {
;     ...
;         for (int i = 0; i < 6 * 465; ++i) g = fmaxf(g, fabsf(p.rpb[(size_t)l * 6 * 465 + i]));
	v_max3_f32 v145, |v100|, |v101|, |v102|
	v_max3_f32 v145, v145, |v103|, |v104|
	v_max3_f32 v145, v145, |v105|, |v106|
	v_max3_f32 v145, v145, |v107|, |v108|
	v_max3_f32 v145, v145, |v109|, |v110|
	v_max3_f32 v145, v145, |v111|, |v112|
	v_max3_f32 v145, v145, |v113|, |v114|
	v_max3_f32 v145, v145, |v115|, |v116|
	v_max3_f32 v145, v145, |v117|, |v118|
	v_max3_f32 v145, v145, |v119|, |v120|
	v_max3_f32 v145, v145, |v121|, |v122|
	v_max3_f32 v145, v145, |v123|, |v124|
	v_max3_f32 v145, v145, |v125|, |v126|
	v_max3_f32 v145, v145, |v127|, |v128|
	v_max3_f32 v145, v145, |v129|, |v130|
	v_max3_f32 v145, v145, |v131|, |v132|
	v_max3_f32 v145, v145, |v133|, |v134|
	v_max3_f32 v145, v145, |v135|, |v136|
	v_max3_f32 v145, v145, |v137|, |v138|
	v_max3_f32 v145, v145, |v139|, |v140|
	v_max3_f32 v145, v145, |v141|, |v142|
	v_max_f32_e64 v145, v145, |v143|
	global_load_dword v100, v96, s[34:35]
	global_load_dword v101, v96, s[34:35] offset:256
	global_load_dword v102, v96, s[34:35] offset:512
	global_load_dword v103, v96, s[34:35] offset:768
	global_load_dword v104, v96, s[34:35] offset:1024
	global_load_dword v105, v96, s[34:35] offset:1280
	global_load_dword v106, v96, s[34:35] offset:1536
	global_load_dword v107, v96, s[34:35] offset:1792
	global_load_dword v108, v96, s[34:35] offset:2048
	global_load_dword v109, v96, s[34:35] offset:2304
	global_load_dword v110, v96, s[34:35] offset:2560
	global_load_dword v111, v96, s[34:35] offset:2816
	global_load_dword v112, v96, s[34:35] offset:3072
	global_load_dword v113, v96, s[34:35] offset:3328
	global_load_dword v114, v96, s[34:35] offset:3584
	global_load_dword v115, v96, s[34:35] offset:3840
	global_load_dword v116, v98, s[34:35]
	global_load_dword v117, v98, s[34:35] offset:256
	global_load_dword v118, v98, s[34:35] offset:512
	global_load_dword v119, v98, s[34:35] offset:768
	global_load_dword v120, v98, s[34:35] offset:1024
	global_load_dword v121, v98, s[34:35] offset:1280
	global_load_dword v122, v98, s[34:35] offset:1536
	global_load_dword v123, v98, s[34:35] offset:1792
	global_load_dword v124, v98, s[34:35] offset:2048
	global_load_dword v125, v98, s[34:35] offset:2304
	global_load_dword v126, v98, s[34:35] offset:2560
	global_load_dword v127, v98, s[34:35] offset:2816
	global_load_dword v128, v98, s[34:35] offset:3072
	global_load_dword v129, v98, s[34:35] offset:3328
	global_load_dword v130, v98, s[34:35] offset:3584
	global_load_dword v131, v98, s[34:35] offset:3840
	global_load_dword v132, v99, s[34:35]
	global_load_dword v133, v99, s[34:35] offset:256
	global_load_dword v134, v99, s[34:35] offset:512
	global_load_dword v135, v99, s[34:35] offset:768
	global_load_dword v136, v99, s[34:35] offset:1024
	global_load_dword v137, v99, s[34:35] offset:1280
	global_load_dword v138, v99, s[34:35] offset:1536
	global_load_dword v139, v99, s[34:35] offset:1792
	global_load_dword v140, v99, s[34:35] offset:2048
	global_load_dword v141, v99, s[34:35] offset:2304
	global_load_dword v142, v99, s[34:35] offset:2560
	global_load_dword v143, v97, s[34:35]
	s_add_u32 s34, s34, 0x2b98
	s_addc_u32 s35, s35, 0
	s_waitcnt vmcnt(0)
	v_max3_f32 v146, |v100|, |v101|, |v102|
	v_max3_f32 v146, v146, |v103|, |v104|
	v_max3_f32 v146, v146, |v105|, |v106|
	v_max3_f32 v146, v146, |v107|, |v108|
	v_max3_f32 v146, v146, |v109|, |v110|
	v_max3_f32 v146, v146, |v111|, |v112|
	v_max3_f32 v146, v146, |v113|, |v114|
	v_max3_f32 v146, v146, |v115|, |v116|
	v_max3_f32 v146, v146, |v117|, |v118|
	v_max3_f32 v146, v146, |v119|, |v120|
	v_max3_f32 v146, v146, |v121|, |v122|
	v_max3_f32 v146, v146, |v123|, |v124|
	v_max3_f32 v146, v146, |v125|, |v126|
	v_max3_f32 v146, v146, |v127|, |v128|
	v_max3_f32 v146, v146, |v129|, |v130|
	v_max3_f32 v146, v146, |v131|, |v132|
	v_max3_f32 v146, v146, |v133|, |v134|
	v_max3_f32 v146, v146, |v135|, |v136|
	v_max3_f32 v146, v146, |v137|, |v138|
	v_max3_f32 v146, v146, |v139|, |v140|
	v_max3_f32 v146, v146, |v141|, |v142|
	v_max_f32_e64 v146, v146, |v143|
	global_load_dword v100, v96, s[34:35]
	global_load_dword v101, v96, s[34:35] offset:256
	global_load_dword v102, v96, s[34:35] offset:512
	global_load_dword v103, v96, s[34:35] offset:768
	global_load_dword v104, v96, s[34:35] offset:1024
	global_load_dword v105, v96, s[34:35] offset:1280
	global_load_dword v106, v96, s[34:35] offset:1536
	global_load_dword v107, v96, s[34:35] offset:1792
	global_load_dword v108, v96, s[34:35] offset:2048
	global_load_dword v109, v96, s[34:35] offset:2304
	global_load_dword v110, v96, s[34:35] offset:2560
	global_load_dword v111, v96, s[34:35] offset:2816
	global_load_dword v112, v96, s[34:35] offset:3072
	global_load_dword v113, v96, s[34:35] offset:3328
	global_load_dword v114, v96, s[34:35] offset:3584
	global_load_dword v115, v96, s[34:35] offset:3840
	global_load_dword v116, v98, s[34:35]
	global_load_dword v117, v98, s[34:35] offset:256
	global_load_dword v118, v98, s[34:35] offset:512
	global_load_dword v119, v98, s[34:35] offset:768
	global_load_dword v120, v98, s[34:35] offset:1024
	global_load_dword v121, v98, s[34:35] offset:1280
	global_load_dword v122, v98, s[34:35] offset:1536
	global_load_dword v123, v98, s[34:35] offset:1792
	global_load_dword v124, v98, s[34:35] offset:2048
	global_load_dword v125, v98, s[34:35] offset:2304
	global_load_dword v126, v98, s[34:35] offset:2560
	global_load_dword v127, v98, s[34:35] offset:2816
	global_load_dword v128, v98, s[34:35] offset:3072
	global_load_dword v129, v98, s[34:35] offset:3328
	global_load_dword v130, v98, s[34:35] offset:3584
	global_load_dword v131, v98, s[34:35] offset:3840
	global_load_dword v132, v99, s[34:35]
	global_load_dword v133, v99, s[34:35] offset:256
	global_load_dword v134, v99, s[34:35] offset:512
	global_load_dword v135, v99, s[34:35] offset:768
	global_load_dword v136, v99, s[34:35] offset:1024
	global_load_dword v137, v99, s[34:35] offset:1280
	global_load_dword v138, v99, s[34:35] offset:1536
	global_load_dword v139, v99, s[34:35] offset:1792
	global_load_dword v140, v99, s[34:35] offset:2048
	global_load_dword v141, v99, s[34:35] offset:2304
	global_load_dword v142, v99, s[34:35] offset:2560
	global_load_dword v143, v97, s[34:35]
	s_waitcnt vmcnt(0)
; DI void prologue_phase(const Params& p, char* smem) {
;     ...
;         for (int i = 0; i < 32; ++i) { a = fmaxf(a, fabsf(p.dqn[l * 32 + i])); bq = fmaxf(bq, fabsf(p.dkn[l * 32 + i])); }
;         for (int i = 0; i < 64; ++i) { c = fmaxf(c, fabsf(p.gqn[l * 64 + i])); d2 = fmaxf(d2, fabsf(p.gkn[l * 64 + i])); e2 = fmaxf(e2, fabsf(p.nqn[l * 64 + i])); f2 = fmaxf(f2, fabsf(p.nkn[l * 64 + i])); }
;         for (int i = 0; i < 6 * 465; ++i) g = fmaxf(g, fabsf(p.rpb[(size_t)l * 6 * 465 + i]));
;         p.lam[8 + l * 4 + 0] = 5.656854249f * a * bq * LOG2E * 1.001f;
;         p.lam[8 + l * 4 + 1] = 8.f * c * d2 * LOG2E * 1.001f;
;         p.lam[8 + l * 4 + 2] = (8.f * e2 * f2 + g) * LOG2E * 1.001f;
;         p.lam[8 + l * 4 + 3] = 8.f * e2 * f2 * LOG2E * 1.001f;
	v_max3_f32 v147, |v100|, |v101|, |v102|
	v_max3_f32 v147, v147, |v103|, |v104|
	v_max3_f32 v147, v147, |v105|, |v106|
	v_max3_f32 v147, v147, |v107|, |v108|
	v_max3_f32 v147, v147, |v109|, |v110|
	v_max3_f32 v147, v147, |v111|, |v112|
	v_max3_f32 v147, v147, |v113|, |v114|
	v_max3_f32 v147, v147, |v115|, |v116|
	v_max3_f32 v147, v147, |v117|, |v118|
	v_max3_f32 v147, v147, |v119|, |v120|
	v_max3_f32 v147, v147, |v121|, |v122|
	v_max3_f32 v147, v147, |v123|, |v124|
	v_max3_f32 v147, v147, |v125|, |v126|
	v_max3_f32 v147, v147, |v127|, |v128|
	v_max3_f32 v147, v147, |v129|, |v130|
	v_max3_f32 v147, v147, |v131|, |v132|
	v_max3_f32 v147, v147, |v133|, |v134|
	v_max3_f32 v147, v147, |v135|, |v136|
	v_max3_f32 v147, v147, |v137|, |v138|
	v_max3_f32 v147, v147, |v139|, |v140|
	v_max3_f32 v147, v147, |v141|, |v142|
	v_max_f32_e64 v147, v147, |v143|
	v_xor_b32_e32 v98, 4, v96
	ds_bpermute_b32 v100, v98, v144
	ds_bpermute_b32 v101, v98, v145
	ds_bpermute_b32 v102, v98, v146
	ds_bpermute_b32 v103, v98, v147
	s_waitcnt lgkmcnt(0)
	v_max_f32_e32 v144, v144, v100
	v_max_f32_e32 v145, v145, v101
	v_max_f32_e32 v146, v146, v102
	v_max_f32_e32 v147, v147, v103
	v_xor_b32_e32 v98, 8, v96
	ds_bpermute_b32 v100, v98, v144
	ds_bpermute_b32 v101, v98, v145
	ds_bpermute_b32 v102, v98, v146
	ds_bpermute_b32 v103, v98, v147
	s_waitcnt lgkmcnt(0)
	v_max_f32_e32 v144, v144, v100
	v_max_f32_e32 v145, v145, v101
	v_max_f32_e32 v146, v146, v102
	v_max_f32_e32 v147, v147, v103
	v_xor_b32_e32 v98, 16, v96
	ds_bpermute_b32 v100, v98, v144
	ds_bpermute_b32 v101, v98, v145
	ds_bpermute_b32 v102, v98, v146
	ds_bpermute_b32 v103, v98, v147
	s_waitcnt lgkmcnt(0)
	v_max_f32_e32 v144, v144, v100
	v_max_f32_e32 v145, v145, v101
	v_max_f32_e32 v146, v146, v102
	v_max_f32_e32 v147, v147, v103
	v_xor_b32_e32 v98, 32, v96
	ds_bpermute_b32 v100, v98, v144
	ds_bpermute_b32 v101, v98, v145
	ds_bpermute_b32 v102, v98, v146
	ds_bpermute_b32 v103, v98, v147
	s_waitcnt lgkmcnt(0)
	v_max_f32_e32 v144, v144, v100
	v_max_f32_e32 v145, v145, v101
	v_max_f32_e32 v146, v146, v102
	v_max_f32_e32 v147, v147, v103
	v_xor_b32_e32 v98, 64, v96
	ds_bpermute_b32 v100, v98, v144
	ds_bpermute_b32 v101, v98, v145
	ds_bpermute_b32 v102, v98, v146
	ds_bpermute_b32 v103, v98, v147
	s_waitcnt lgkmcnt(0)
	v_max_f32_e32 v144, v144, v100
	v_max_f32_e32 v145, v145, v101
	v_max_f32_e32 v146, v146, v102
	v_max_f32_e32 v147, v147, v103
	v_xor_b32_e32 v98, 128, v96
	ds_bpermute_b32 v100, v98, v144
	ds_bpermute_b32 v101, v98, v145
	ds_bpermute_b32 v102, v98, v146
	ds_bpermute_b32 v103, v98, v147
	s_waitcnt lgkmcnt(0)
	v_max_f32_e32 v144, v144, v100
	v_max_f32_e32 v145, v145, v101
	v_max_f32_e32 v146, v146, v102
	v_max_f32_e32 v147, v147, v103
	s_mov_b64 exec, s[8:9]
	v_cmp_eq_u32_e32 vcc, 1, v64
	s_nop 1
	v_cndmask_b32_e32 v72, v144, v145, vcc
	v_cmp_eq_u32_e32 vcc, 2, v64
	s_nop 1
	v_cndmask_b32_e32 v72, v72, v146, vcc
	v_cmp_eq_u32_e32 vcc, 3, v64
	s_nop 1
	v_cndmask_b32_e32 v72, v72, v147, vcc
	s_movk_i32 s61, 0x800
	v_max3_f32 v20, |v20|, 0, |v21|
	v_max3_f32 v20, v20, |v22|, |v23|
	v_max3_f32 v12, v20, |v12|, |v13|
	v_max3_f32 v12, v12, |v14|, |v15|
	v_max3_f32 v4, v12, |v4|, |v5|
	v_max3_f32 v4, v4, |v6|, |v7|
	v_max3_f32 v0, v4, |v0|, |v1|
	v_max3_f32 v0, v0, |v2|, |v3|
	v_max3_f32 v0, v0, |v52|, |v53|
	v_max3_f32 v0, v0, |v54|, |v55|
	v_max3_f32 v0, v0, |v44|, |v45|
	v_max3_f32 v0, v0, |v46|, |v47|
	v_max3_f32 v0, v0, |v36|, |v37|
	v_max3_f32 v0, v0, |v38|, |v39|
	v_max3_f32 v0, v0, |v32|, |v33|
	v_max3_f32 v68, v0, |v34|, |v35|
	v_max3_f32 v0, |v28|, 0, |v29|
	v_max3_f32 v0, v0, |v30|, |v31|
	v_max3_f32 v0, v0, |v24|, |v25|
	v_max3_f32 v0, v0, |v26|, |v27|
	v_max3_f32 v0, v0, |v16|, |v17|
	v_max3_f32 v0, v0, |v18|, |v19|
	v_max3_f32 v0, v0, |v8|, |v9|
	v_max3_f32 v0, v0, |v10|, |v11|
	v_max3_f32 v0, v0, |v60|, |v61|
	v_max3_f32 v0, v0, |v62|, |v63|
	v_max3_f32 v0, v0, |v56|, |v57|
	v_max3_f32 v0, v0, |v58|, |v59|
	v_max3_f32 v0, v0, |v48|, |v49|
	v_max3_f32 v0, v0, |v50|, |v51|
	v_max3_f32 v0, v0, |v40|, |v41|
	v_max3_f32 v66, v0, |v42|, |v43|
	v_lshlrev_b32_e32 v0, 2, v64
	v_ashrrev_i32_e32 v1, 31, v0
	v_lshl_add_u64 v[4:5], v[0:1], 2, s[6:7]
	s_mov_b32 s6, 0x40b504f3
	s_mov_b32 s7, 0x41000000
	v_pk_mul_f32 v[0:1], v[68:69], s[6:7]
	v_mul_f32_e32 v2, 0x41000000, v65
	v_pk_mul_f32 v[0:1], v[0:1], v[66:67]
	s_mov_b32 s6, 0x3fb8aa3b
	v_mul_f32_e32 v73, v2, v78
	v_fmac_f32_e32 v72, v2, v78
	v_pk_mul_f32 v[0:1], v[0:1], s[6:7] op_sel_hi:[1,0]
	s_mov_b32 s8, 0x3f8020c5
	v_pk_mul_f32 v[2:3], v[72:73], s[6:7] op_sel_hi:[1,0]
	v_pk_mul_f32 v[0:1], v[0:1], s[8:9] op_sel_hi:[1,0]
	v_pk_mul_f32 v[2:3], v[2:3], s[8:9] op_sel_hi:[1,0]
	global_store_dwordx4 v[4:5], v[0:3], off offset:32
